# X13: X10 + Mamba-2 dt MFMA block hand-scheduled (all 40 fragment loads up front, then 32 MFMAs) instead of 40 serialized load-wait-MFMA round trips
# speedup vs baseline: 1.0030x; 1.0016x over previous
; #define LAS __attribute__((address_space(3)))
; __device__ __forceinline__ void sd_p1_unit(const Args& a, unsigned char* ws, int l, const rs_t* rowss, int unit, LAS unsigned char* lds, int tid_in) {
;     ...
;     const int chunk = unit & 255, b = unit >> 8, lane = tid & 63, wave = tid >> 6, fr = lane & 15, g = lane >> 4;
;     const size_t row0 = (size_t)b * SEQ + (size_t)chunk * 64;
;     LAS float* dtl = (LAS float*)lds; LAS float* acs = dtl + 512;
;     LAS float* part = (LAS float*)(lds + 4096);
;     LAS bf16* XT = (LAS bf16*)(lds + 4096); LAS bf16* BT = XT + 512 * SD_TS;
;     { pg8::f32x4 acc[4];
; #pragma unroll
;       for (int tt = 0; tt < 4; ++tt) acc[tt] = (pg8::f32x4){0.f, 0.f, 0.f, 0.f};
; #pragma unroll 4
;       for (int ks = 0; ks < 8; ++ks) { const int k = 256 * wave + 32 * ks + 8 * g;
;           bf16x8_t bfr = {0, 0, 0, 0, 0, 0, 0, 0}; if (fr < 8) bfr = *(const bf16x8_t*)(wdtb + fr * DM + k);
; #pragma unroll
;           for (int tt = 0; tt < 4; ++tt) { const bf16x8_t af = *(const bf16x8_t*)(xb + (row0 + 16 * tt + fr) * DM + k); acc[tt] = __builtin_amdgcn_mfma_f32_16x16x32_bf16(af, bfr, acc[tt], 0, 0, 0); } }
.LBB0_767:
	s_ashr_i32 s22, s54, 8
	s_and_b32 s2, s54, 0xff
	s_ashr_i32 s23, s22, 31
	v_mov_b32_e32 v34, v210
	s_lshl_b32 s3, s2, 6
	s_lshl_b64 s[36:37], s[22:23], 14
	s_or_b32 s36, s36, s3
	v_and_b32_e32 v2, 15, v34
	v_bfe_u32 v3, v34, 4, 2
	v_ashrrev_i32_e32 v36, 6, v34
	v_lshlrev_b32_e32 v10, 3, v3
	v_or_b32_e32 v6, s36, v2
	v_mov_b32_e32 v7, s37
	v_or_b32_e32 v8, 16, v6
	v_mov_b32_e32 v9, s37
	v_lshl_or_b32 v56, v36, 8, v10
	v_lshlrev_b32_e32 v4, 12, v2
	v_lshlrev_b64 v[40:41], 12, v[6:7]
	v_lshlrev_b64 v[42:43], 12, v[8:9]
	v_or_b32_e32 v8, 32, v6
	v_or_b32_e32 v6, 48, v6
	v_ashrrev_i32_e32 v57, 31, v56
	v_lshlrev_b64 v[46:47], 12, v[6:7]
	v_lshl_add_u64 v[6:7], v[56:57], 1, v[4:5]
	v_lshlrev_b64 v[44:45], 12, v[8:9]
	v_lshl_add_u64 v[58:59], s[50:51], 0, v[6:7]
	v_mov_b32_e32 v6, 0
	v_cmp_gt_u32_e32 vcc, 8, v2
	v_lshl_add_u64 v[38:39], s[40:41], 0, v[4:5]
	v_lshl_add_u64 v[48:49], s[96:97], 0, v[40:41]
	v_lshl_add_u64 v[50:51], s[96:97], 0, v[42:43]
	v_lshl_add_u64 v[52:53], s[96:97], 0, v[44:45]
	v_lshl_add_u64 v[54:55], s[96:97], 0, v[46:47]
	v_lshl_add_u64 v[6:7], v[56:57], 1, v[38:39]
	v_lshl_add_u64 v[8:9], v[56:57], 1, v[48:49]
	v_lshl_add_u64 v[10:11], v[56:57], 1, v[50:51]
	v_lshl_add_u64 v[12:13], v[56:57], 1, v[52:53]
	v_lshl_add_u64 v[14:15], v[56:57], 1, v[54:55]
	v_mov_b64_e32 v[22:23], 0
	v_mov_b64_e32 v[24:25], 0
	v_mov_b64_e32 v[26:27], 0
	v_mov_b64_e32 v[28:29], 0
	v_mov_b64_e32 v[30:31], 0
	v_mov_b64_e32 v[32:33], 0
	v_mov_b64_e32 v[60:61], 0
	v_mov_b64_e32 v[62:63], 0
	v_mov_b64_e32 v[64:65], 0
	v_mov_b64_e32 v[66:67], 0
	v_mov_b64_e32 v[68:69], 0
	v_mov_b64_e32 v[70:71], 0
	v_mov_b64_e32 v[72:73], 0
	v_mov_b64_e32 v[74:75], 0
	v_mov_b64_e32 v[76:77], 0
	v_mov_b64_e32 v[78:79], 0
	s_and_saveexec_b64 s[22:23], vcc
	global_load_dwordx4 v[22:25], v[6:7], off
	global_load_dwordx4 v[26:29], v[6:7], off offset:64
	global_load_dwordx4 v[30:33], v[6:7], off offset:128
	global_load_dwordx4 v[60:63], v[6:7], off offset:192
	global_load_dwordx4 v[64:67], v[6:7], off offset:256
	global_load_dwordx4 v[68:71], v[6:7], off offset:320
	global_load_dwordx4 v[72:75], v[6:7], off offset:384
	global_load_dwordx4 v[76:79], v[6:7], off offset:448
	s_or_b64 exec, exec, s[22:23]
	global_load_dwordx4 v[80:83], v[8:9], off
	global_load_dwordx4 v[84:87], v[10:11], off
	global_load_dwordx4 v[88:91], v[12:13], off
	global_load_dwordx4 v[92:95], v[14:15], off
	global_load_dwordx4 v[96:99], v[8:9], off offset:64
	global_load_dwordx4 v[100:103], v[10:11], off offset:64
	global_load_dwordx4 v[104:107], v[12:13], off offset:64
	global_load_dwordx4 v[108:111], v[14:15], off offset:64
	global_load_dwordx4 v[112:115], v[8:9], off offset:128
	global_load_dwordx4 v[116:119], v[10:11], off offset:128
	global_load_dwordx4 v[120:123], v[12:13], off offset:128
	global_load_dwordx4 v[124:127], v[14:15], off offset:128
	global_load_dwordx4 v[128:131], v[8:9], off offset:192
	global_load_dwordx4 v[132:135], v[10:11], off offset:192
	global_load_dwordx4 v[136:139], v[12:13], off offset:192
	global_load_dwordx4 v[144:147], v[14:15], off offset:192
	global_load_dwordx4 v[148:151], v[8:9], off offset:256
	global_load_dwordx4 v[152:155], v[10:11], off offset:256
	global_load_dwordx4 v[168:171], v[12:13], off offset:256
	global_load_dwordx4 v[172:175], v[14:15], off offset:256
	global_load_dwordx4 v[176:179], v[8:9], off offset:320
	global_load_dwordx4 v[180:183], v[10:11], off offset:320
	global_load_dwordx4 v[184:187], v[12:13], off offset:320
	global_load_dwordx4 v[188:191], v[14:15], off offset:320
	global_load_dwordx4 v[212:215], v[8:9], off offset:384
	global_load_dwordx4 v[216:219], v[10:11], off offset:384
	global_load_dwordx4 v[220:223], v[12:13], off offset:384
	global_load_dwordx4 v[224:227], v[14:15], off offset:384
	global_load_dwordx4 v[228:231], v[8:9], off offset:448
	global_load_dwordx4 v[232:235], v[10:11], off offset:448
	global_load_dwordx4 v[236:239], v[12:13], off offset:448
	global_load_dwordx4 v[240:243], v[14:15], off offset:448
	s_waitcnt vmcnt(28)
	v_mfma_f32_16x16x32_bf16 v[18:21], v[80:83], v[22:25], 0
	v_mfma_f32_16x16x32_bf16 v[14:17], v[84:87], v[22:25], 0
	v_mfma_f32_16x16x32_bf16 v[10:13], v[88:91], v[22:25], 0
	v_mfma_f32_16x16x32_bf16 v[6:9], v[92:95], v[22:25], 0
	s_waitcnt vmcnt(24)
	v_mfma_f32_16x16x32_bf16 v[18:21], v[96:99], v[26:29], v[18:21]
	v_mfma_f32_16x16x32_bf16 v[14:17], v[100:103], v[26:29], v[14:17]
	v_mfma_f32_16x16x32_bf16 v[10:13], v[104:107], v[26:29], v[10:13]
	v_mfma_f32_16x16x32_bf16 v[6:9], v[108:111], v[26:29], v[6:9]
	s_waitcnt vmcnt(20)
	v_mfma_f32_16x16x32_bf16 v[18:21], v[112:115], v[30:33], v[18:21]
	v_mfma_f32_16x16x32_bf16 v[14:17], v[116:119], v[30:33], v[14:17]
	v_mfma_f32_16x16x32_bf16 v[10:13], v[120:123], v[30:33], v[10:13]
	v_mfma_f32_16x16x32_bf16 v[6:9], v[124:127], v[30:33], v[6:9]
	s_waitcnt vmcnt(16)
	v_mfma_f32_16x16x32_bf16 v[18:21], v[128:131], v[60:63], v[18:21]
	v_mfma_f32_16x16x32_bf16 v[14:17], v[132:135], v[60:63], v[14:17]
	v_mfma_f32_16x16x32_bf16 v[10:13], v[136:139], v[60:63], v[10:13]
	v_mfma_f32_16x16x32_bf16 v[6:9], v[144:147], v[60:63], v[6:9]
	s_waitcnt vmcnt(12)
	v_mfma_f32_16x16x32_bf16 v[18:21], v[148:151], v[64:67], v[18:21]
	v_mfma_f32_16x16x32_bf16 v[14:17], v[152:155], v[64:67], v[14:17]
	v_mfma_f32_16x16x32_bf16 v[10:13], v[168:171], v[64:67], v[10:13]
	v_mfma_f32_16x16x32_bf16 v[6:9], v[172:175], v[64:67], v[6:9]
	s_waitcnt vmcnt(8)
	v_mfma_f32_16x16x32_bf16 v[18:21], v[176:179], v[68:71], v[18:21]
	v_mfma_f32_16x16x32_bf16 v[14:17], v[180:183], v[68:71], v[14:17]
	v_mfma_f32_16x16x32_bf16 v[10:13], v[184:187], v[68:71], v[10:13]
	v_mfma_f32_16x16x32_bf16 v[6:9], v[188:191], v[68:71], v[6:9]
	s_waitcnt vmcnt(4)
	v_mfma_f32_16x16x32_bf16 v[18:21], v[212:215], v[72:75], v[18:21]
	v_mfma_f32_16x16x32_bf16 v[14:17], v[216:219], v[72:75], v[14:17]
	v_mfma_f32_16x16x32_bf16 v[10:13], v[220:223], v[72:75], v[10:13]
	v_mfma_f32_16x16x32_bf16 v[6:9], v[224:227], v[72:75], v[6:9]
	s_waitcnt vmcnt(0)
	v_mfma_f32_16x16x32_bf16 v[18:21], v[228:231], v[76:79], v[18:21]
	v_mfma_f32_16x16x32_bf16 v[14:17], v[232:235], v[76:79], v[14:17]
	v_mfma_f32_16x16x32_bf16 v[10:13], v[236:239], v[76:79], v[10:13]
	v_mfma_f32_16x16x32_bf16 v[6:9], v[240:243], v[76:79], v[6:9]
	s_movk_i32 s3, 0x100
	s_nop 7
